# L2 code warm-up: at every seam each non-last workgroup loads 1KB of the next 32KB of program text (s_getpc-relative) so the next phase's instruction-cache misses hit L2
# speedup vs baseline: 1.0093x; 1.0093x over previous
; __device__ __forceinline__ int lane_id_() { int l; asm volatile("v_mbcnt_lo_u32_b32 %0, -1, 0\n\tv_mbcnt_hi_u32_b32 %0, -1, %0" : "=v"(l)); return l; }
; __device__ __forceinline__ unsigned xb_ld(unsigned* p)              { return __hip_atomic_load(p, __ATOMIC_RELAXED, __HIP_MEMORY_SCOPE_AGENT); }
; __device__ __forceinline__ unsigned xb_add(unsigned* p, unsigned v) { return __hip_atomic_fetch_add(p, v, __ATOMIC_RELAXED, __HIP_MEMORY_SCOPE_AGENT); }
; #define XB_SPIN(cond, bar) do { unsigned _sp = 0; while (cond) { __builtin_amdgcn_s_sleep(1); \
;     if ((++_sp & 255u) == 0u) { if (xb_ld(&(bar)[XB_TMO])) break; if (_sp > XB_SPIN_CAP) { atomicAdd(&(bar)[XB_TMO], 1u); break; } } } } while (0)
; __device__ __forceinline__ void xcd_barrier(const XcdBarrier& b, int wave_s) {
;     ...
;     if (wave_s == 0 && lane_id_() == 0) {
;         unsigned* bar = b.bar;
;         __builtin_amdgcn_s_waitcnt(0);
;         unsigned nloc = b.st[0], nx = b.st[1];
;         if (nloc == 0u) { xcd_barrier_complete(bar, b.x, nloc, nx); b.st[0] = nloc; b.st[1] = nx; }
;         const unsigned old = xb_add(&bar[XB_XSUB(b.x)], 1u);
;         const unsigned gen = old / nloc;
;         if (old + 1u == (gen + 1u) * nloc) {
;             __builtin_amdgcn_fence(__ATOMIC_RELEASE, "agent");
;             asm volatile("s_waitcnt vmcnt(0)" ::: "memory");
;             const unsigned og = xb_add(&bar[XB_TOP], 1u);
;             const unsigned tg = og / nx;
;             if (og + 1u == (tg + 1u) * nx) xb_add(&bar[XB_TOPGEN], 1u);
;             else XB_SPIN(xb_ld(&bar[XB_TOPGEN]) == tg, bar);
;             __builtin_amdgcn_fence(__ATOMIC_ACQUIRE, "agent");
;             xb_add(&bar[XB_XGEN(b.x)], 1u);
;             asm volatile("s_waitcnt vmcnt(0)" ::: "memory");
;         } else {
;             XB_SPIN(xb_ld(&bar[XB_XGEN(b.x)]) == gen, bar);
.Llw_S1:
	v_mov_b32_e32 v1, s98
	s_getpc_b64 s[98:99]
	s_lshr_b32 s100, s33, 3
	s_and_b32 s100, s100, 31
	s_lshl_b32 s100, s100, 10
	s_add_u32 s98, s98, s100
	s_addc_u32 s99, s99, 0
	s_mov_b64 exec, -1
	v_mbcnt_lo_u32_b32 v4, -1, 0
	v_mbcnt_hi_u32_b32 v4, -1, v4
	v_lshlrev_b32_e32 v4, 4, v4
	global_load_dwordx4 v[6:9], v4, s[98:99]
	s_mov_b64 exec, 1
	v_readfirstlane_b32 s98, v1
	s_nop 3

; __device__ __forceinline__ int lane_id_() { int l; asm volatile("v_mbcnt_lo_u32_b32 %0, -1, 0\n\tv_mbcnt_hi_u32_b32 %0, -1, %0" : "=v"(l)); return l; }
; __device__ __forceinline__ unsigned xb_ld(unsigned* p)              { return __hip_atomic_load(p, __ATOMIC_RELAXED, __HIP_MEMORY_SCOPE_AGENT); }
; __device__ __forceinline__ unsigned xb_add(unsigned* p, unsigned v) { return __hip_atomic_fetch_add(p, v, __ATOMIC_RELAXED, __HIP_MEMORY_SCOPE_AGENT); }
; #define XB_SPIN(cond, bar) do { unsigned _sp = 0; while (cond) { __builtin_amdgcn_s_sleep(1); \
;     if ((++_sp & 255u) == 0u) { if (xb_ld(&(bar)[XB_TMO])) break; if (_sp > XB_SPIN_CAP) { atomicAdd(&(bar)[XB_TMO], 1u); break; } } } } while (0)
; __device__ __forceinline__ void xcd_barrier(const XcdBarrier& b, int wave_s) {
;     ...
;     if (wave_s == 0 && lane_id_() == 0) {
;         unsigned* bar = b.bar;
;         __builtin_amdgcn_s_waitcnt(0);
;         unsigned nloc = b.st[0], nx = b.st[1];
;         if (nloc == 0u) { xcd_barrier_complete(bar, b.x, nloc, nx); b.st[0] = nloc; b.st[1] = nx; }
;         const unsigned old = xb_add(&bar[XB_XSUB(b.x)], 1u);
;         const unsigned gen = old / nloc;
;         if (old + 1u == (gen + 1u) * nloc) {
;             __builtin_amdgcn_fence(__ATOMIC_RELEASE, "agent");
;             asm volatile("s_waitcnt vmcnt(0)" ::: "memory");
;             const unsigned og = xb_add(&bar[XB_TOP], 1u);
;             const unsigned tg = og / nx;
;             if (og + 1u == (tg + 1u) * nx) xb_add(&bar[XB_TOPGEN], 1u);
;             else XB_SPIN(xb_ld(&bar[XB_TOPGEN]) == tg, bar);
;             __builtin_amdgcn_fence(__ATOMIC_ACQUIRE, "agent");
;             xb_add(&bar[XB_XGEN(b.x)], 1u);
;             asm volatile("s_waitcnt vmcnt(0)" ::: "memory");
;         } else {
;             XB_SPIN(xb_ld(&bar[XB_XGEN(b.x)]) == gen, bar);
.Llw_S4:
	v_mov_b32_e32 v1, s98
	s_getpc_b64 s[98:99]
	s_lshr_b32 s100, s33, 3
	s_and_b32 s100, s100, 31
	s_lshl_b32 s100, s100, 10
	s_add_u32 s98, s98, s100
	s_addc_u32 s99, s99, 0
	s_mov_b64 exec, -1
	v_mbcnt_lo_u32_b32 v4, -1, 0
	v_mbcnt_hi_u32_b32 v4, -1, v4
	v_lshlrev_b32_e32 v4, 4, v4
	global_load_dwordx4 v[6:9], v4, s[98:99]
	s_mov_b64 exec, 1
	v_readfirstlane_b32 s98, v1
	s_nop 3
	s_mov_b32 s99, 0
